# v101 + ssd_sample_unit: recurrent-state loads issued one stage earlier and a_log with the unit's first loads
# speedup vs baseline: 1.0058x; 1.0058x over previous
; __device__ __forceinline__ void ssd_sample_unit(const Params& p, int unit, float* lds) {
;     ...
;     const int pp = tid >> 3, nn = tid & 7;
;     const size_t soff = ((size_t)(b * 16 + h) * 64 + pp) * 128 + nn * 16;
;     const float* hp = p.state_ssm + soff;
;     float4 h0 = *(const float4*)hp, h1 = *(const float4*)(hp + 4), h2 = *(const float4*)(hp + 8), h3 = *(const float4*)(hp + 12);
;     float myoff = 0.f;
; #pragma unroll
;     for (int l = 0; l < 8; ++l) {
;         const float* cp = Cf + l * 128 + nn * 16;
;         float part = cp[0] * h0.x + cp[1] * h0.y + cp[2] * h0.z + cp[3] * h0.w + cp[4] * h1.x + cp[5] * h1.y + cp[6] * h1.z + cp[7] * h1.w
;                    + cp[8] * h2.x + cp[9] * h2.y + cp[10] * h2.z + cp[11] * h2.w + cp[12] * h3.x + cp[13] * h3.y + cp[14] * h3.z + cp[15] * h3.w;
;         part += __shfl_xor(part, 1); part += __shfl_xor(part, 2); part += __shfl_xor(part, 4);
;         if (nn == l) myoff = part;
;     }
;     const float cs7 = csb[7], e7 = __expf(cs7);
;     h0.x *= e7; h0.y *= e7; h0.z *= e7; h0.w *= e7; h1.x *= e7; h1.y *= e7; h1.z *= e7; h1.w *= e7;
;     h2.x *= e7; h2.y *= e7; h2.z *= e7; h2.w *= e7; h3.x *= e7; h3.y *= e7; h3.z *= e7; h3.w *= e7;
; #pragma unroll
;     for (int l = 0; l < 8; ++l) {
;         const float w = __expf(cs7 - csb[l]) * dtb[l] * xsf[l * 64 + pp];
;         const float* bp = Bf + l * 128 + nn * 16;
;         h0.x += bp[0] * w; h0.y += bp[1] * w; h0.z += bp[2] * w; h0.w += bp[3] * w; h1.x += bp[4] * w; h1.y += bp[5] * w; h1.z += bp[6] * w; h1.w += bp[7] * w;
;         h2.x += bp[8] * w; h2.y += bp[9] * w; h2.z += bp[10] * w; h2.w += bp[11] * w; h3.x += bp[12] * w; h3.y += bp[13] * w; h3.z += bp[14] * w; h3.w += bp[15] * w;
;     }
.LBB0_405:
	s_or_b64 exec, exec, s[28:29]
	v_lshl_add_u64 v[16:17], v[186:187], 0, s[38:39]
	s_waitcnt lgkmcnt(0)
	s_barrier
	s_waitcnt vmcnt(0)
	v_mov_b64_e32 v[44:45], v[216:217]
	v_mov_b64_e32 v[46:47], v[218:219]
	v_mov_b64_e32 v[36:37], v[220:221]
	v_mov_b64_e32 v[38:39], v[222:223]
	ds_read_b128 v[140:143], v203 offset:4096
	ds_read_b128 v[108:111], v203 offset:4112
	ds_read_b128 v[76:79], v203 offset:4128
	ds_read_b128 v[60:63], v203 offset:4144
	ds_read_b128 v[144:147], v203 offset:4608
	ds_read_b128 v[112:115], v203 offset:4624
	ds_read_b128 v[80:83], v203 offset:4640
	ds_read_b128 v[56:59], v203 offset:4656
	ds_read_b128 v[148:151], v203 offset:5120
	ds_read_b128 v[116:119], v203 offset:5136
	ds_read_b128 v[84:87], v203 offset:5152
	ds_read_b128 v[24:27], v203 offset:5168
	ds_read_b128 v[152:155], v203 offset:5632
	ds_read_b128 v[120:123], v203 offset:5648
	ds_read_b128 v[88:91], v203 offset:5664
	ds_read_b128 v[12:15], v203 offset:5680
	ds_read_b128 v[156:159], v203 offset:6144
	ds_read_b128 v[124:127], v203 offset:6160
	ds_read_b128 v[92:95], v203 offset:6176
	ds_read_b128 v[20:23], v203 offset:6192
	ds_read_b128 v[160:163], v203 offset:6656
	ds_read_b128 v[128:131], v203 offset:6672
	ds_read_b128 v[96:99], v203 offset:6688
	ds_read_b128 v[0:3], v203 offset:6704
	ds_read_b128 v[164:167], v203 offset:7168
	ds_read_b128 v[132:135], v203 offset:7184
	ds_read_b128 v[100:103], v203 offset:7200
	ds_read_b128 v[8:11], v203 offset:7216
	ds_read_b128 v[168:171], v203 offset:7680
	v_mov_b64_e32 v[4:5], v[228:229]
	v_mov_b64_e32 v[6:7], v[230:231]
	v_mov_b64_e32 v[52:53], v[224:225]
	v_mov_b64_e32 v[54:55], v[226:227]
	ds_read_b128 v[136:139], v203 offset:7696
	ds_read_b128 v[104:107], v203 offset:7712
	ds_read_b128 v[48:51], v183 offset:10496
	ds_read_b128 v[32:35], v183 offset:10512
	ds_read_b128 v[40:43], v183 offset:10528
	ds_read_b128 v[28:31], v183 offset:10544
	ds_read2st64_b32 v[190:191], v201 offset0:32 offset1:33
	ds_read_b128 v[16:19], v203 offset:7728
	ds_read_b128 v[72:75], v207
	ds_read_b128 v[68:71], v207 offset:16
	ds_read_b128 v[64:67], v207 offset:32
	ds_read_b32 v210, v202 offset:10496
	v_lshl_add_u64 v[192:193], v[184:185], 0, s[38:39]
	s_lshl_b32 s4, s52, 1
	v_mov_b32_e32 v189, v183
	s_add_i32 s41, s41, s92
	s_waitcnt vmcnt(3) lgkmcnt(14)
	v_mul_f32_e32 v141, v45, v141
	v_fmac_f32_e32 v141, v44, v140
	v_fmac_f32_e32 v141, v46, v142
	v_fmac_f32_e32 v141, v47, v143
	v_mul_f32_e32 v161, v45, v161
	s_waitcnt vmcnt(2)
	v_fmac_f32_e32 v141, v36, v108
	v_fmac_f32_e32 v161, v44, v160
	v_fmac_f32_e32 v141, v37, v109
	v_fmac_f32_e32 v161, v46, v162
	v_fmac_f32_e32 v141, v38, v110
	v_fmac_f32_e32 v161, v47, v163
	v_fmac_f32_e32 v141, v39, v111
	v_fmac_f32_e32 v161, v36, v128
	s_waitcnt vmcnt(0)
	v_fmac_f32_e32 v141, v52, v76
	v_fmac_f32_e32 v161, v37, v129
	v_fmac_f32_e32 v141, v53, v77
	v_fmac_f32_e32 v161, v38, v130
	v_fmac_f32_e32 v141, v54, v78
	v_fmac_f32_e32 v161, v39, v131
	v_fmac_f32_e32 v141, v55, v79
	v_fmac_f32_e32 v161, v52, v96
	v_fmac_f32_e32 v141, v4, v60
	v_fmac_f32_e32 v161, v53, v97
	v_fmac_f32_e32 v141, v5, v61
	v_fmac_f32_e32 v161, v54, v98
	v_fmac_f32_e32 v141, v6, v62
	v_fmac_f32_e32 v161, v55, v99
	v_fmac_f32_e32 v141, v7, v63
	v_mul_f32_e32 v212, v45, v149
	s_waitcnt lgkmcnt(12)
	v_mul_f32_e32 v169, v45, v169
	v_fmac_f32_e32 v161, v4, v0
	ds_bpermute_b32 v0, v204, v141
	v_fmac_f32_e32 v212, v44, v148
	v_fmac_f32_e32 v169, v44, v168
	v_fmac_f32_e32 v212, v46, v150
	v_fmac_f32_e32 v169, v46, v170
	v_fmac_f32_e32 v212, v47, v151
	v_fmac_f32_e32 v169, v47, v171
	v_mul_f32_e32 v153, v45, v153
	v_fmac_f32_e32 v212, v36, v116
	s_waitcnt lgkmcnt(12)
	v_fmac_f32_e32 v169, v36, v136
	v_fmac_f32_e32 v153, v44, v152
	v_fmac_f32_e32 v212, v37, v117
	v_fmac_f32_e32 v169, v37, v137
	s_waitcnt lgkmcnt(0)
	v_add_f32_e32 v152, v141, v0
	v_sub_f32_e32 v0, v35, v48
	v_fmac_f32_e32 v212, v38, v118
	v_fmac_f32_e32 v169, v38, v138
	v_mul_f32_e32 v0, 0x3fb8aa3b, v0
	v_fmac_f32_e32 v212, v39, v119
	v_fmac_f32_e32 v169, v39, v139
	v_fmac_f32_e32 v161, v5, v1
	v_exp_f32_e32 v1, v0
	v_fmac_f32_e32 v212, v52, v84
	v_fmac_f32_e32 v169, v52, v104
	v_fmac_f32_e32 v212, v53, v85
	v_fmac_f32_e32 v169, v53, v105
	v_mul_f32_e32 v0, 0x3fb8aa3b, v35
	v_fmac_f32_e32 v212, v54, v86
	v_fmac_f32_e32 v169, v54, v106
	v_exp_f32_e32 v0, v0
	v_mul_f32_e32 v211, v45, v145
	v_fmac_f32_e32 v212, v55, v87
	v_fmac_f32_e32 v169, v55, v107
	v_mul_f32_e32 v1, v40, v1
	v_fmac_f32_e32 v211, v44, v144
	v_fmac_f32_e32 v212, v4, v24
	v_fmac_f32_e32 v169, v4, v16
	v_mul_f32_e32 v16, v190, v1
	v_sub_f32_e32 v1, v35, v35
	v_mul_f32_e32 v157, v45, v157
	v_mul_f32_e32 v165, v45, v165
	v_fmac_f32_e32 v211, v46, v146
	v_fmac_f32_e32 v212, v5, v25
	v_mul_f32_e32 v1, 0x3fb8aa3b, v1
	v_pk_mul_f32 v[24:25], v[72:73], v[16:17] op_sel_hi:[1,0]
	v_fmac_f32_e32 v157, v44, v156
	v_fmac_f32_e32 v165, v44, v164
	v_fmac_f32_e32 v211, v47, v147
	v_exp_f32_e32 v156, v1
	v_pk_fma_f32 v[24:25], v[44:45], v[0:1], v[24:25] op_sel_hi:[1,0,1]
	v_sub_f32_e32 v1, v35, v49
	v_fmac_f32_e32 v153, v46, v154
	v_fmac_f32_e32 v157, v46, v158
	v_fmac_f32_e32 v165, v46, v166
	v_fmac_f32_e32 v211, v36, v112
	v_mul_f32_e32 v1, 0x3fb8aa3b, v1
	v_fmac_f32_e32 v153, v47, v155
	v_fmac_f32_e32 v157, v47, v159
	v_fmac_f32_e32 v165, v47, v167
	v_fmac_f32_e32 v211, v37, v113
	v_exp_f32_e32 v1, v1
	v_fmac_f32_e32 v153, v36, v120
	v_fmac_f32_e32 v157, v36, v124
	v_fmac_f32_e32 v165, v36, v132
	v_fmac_f32_e32 v211, v38, v114
	v_fmac_f32_e32 v153, v37, v121
	v_fmac_f32_e32 v157, v37, v125
	v_fmac_f32_e32 v165, v37, v133
	v_fmac_f32_e32 v211, v39, v115
	ds_read_b128 v[108:111], v207 offset:48
	ds_read_b128 v[112:115], v207 offset:512
	v_fmac_f32_e32 v153, v38, v122
	v_fmac_f32_e32 v157, v38, v126
	v_fmac_f32_e32 v165, v38, v134
	v_pk_mul_f32 v[44:45], v[74:75], v[16:17] op_sel_hi:[1,0]
	v_fmac_f32_e32 v153, v39, v123
	v_fmac_f32_e32 v157, v39, v127
	v_fmac_f32_e32 v165, v39, v135
	v_fmac_f32_e32 v211, v52, v80
	v_pk_fma_f32 v[44:45], v[46:47], v[0:1], v[44:45] op_sel_hi:[1,0,1]
	v_pk_mul_f32 v[46:47], v[16:17], v[68:69] op_sel_hi:[0,1]
	v_fmac_f32_e32 v211, v53, v81
	v_fmac_f32_e32 v153, v52, v88
	v_fmac_f32_e32 v157, v52, v92
	v_fmac_f32_e32 v165, v52, v100
	v_pk_fma_f32 v[36:37], v[36:37], v[0:1], v[46:47] op_sel_hi:[1,0,1]
	v_mul_f32_e32 v1, v41, v1
	v_pk_mul_f32 v[46:47], v[16:17], v[64:65] op_sel_hi:[0,1]
	v_fmac_f32_e32 v153, v53, v89
	v_fmac_f32_e32 v157, v53, v93
	v_fmac_f32_e32 v165, v53, v101
	v_fmac_f32_e32 v211, v54, v82
	v_pk_mul_f32 v[40:41], v[16:17], v[70:71] op_sel_hi:[0,1]
	v_pk_fma_f32 v[46:47], v[52:53], v[0:1], v[46:47] op_sel_hi:[1,0,1]
	v_pk_mul_f32 v[48:49], v[16:17], v[66:67] op_sel_hi:[0,1]
	s_waitcnt lgkmcnt(1)
; __device__ __forceinline__ void ssd_sample_unit(const Params& p, int unit, float* lds) {
;     ...
;     const float cs7 = csb[7], e7 = __expf(cs7);
;     h0.x *= e7; h0.y *= e7; h0.z *= e7; h0.w *= e7; h1.x *= e7; h1.y *= e7; h1.z *= e7; h1.w *= e7;
;     h2.x *= e7; h2.y *= e7; h2.z *= e7; h2.w *= e7; h3.x *= e7; h3.y *= e7; h3.z *= e7; h3.w *= e7;
; #pragma unroll
;     for (int l = 0; l < 8; ++l) {
;         const float w = __expf(cs7 - csb[l]) * dtb[l] * xsf[l * 64 + pp];
;         const float* bp = Bf + l * 128 + nn * 16;
;         h0.x += bp[0] * w; h0.y += bp[1] * w; h0.z += bp[2] * w; h0.w += bp[3] * w; h1.x += bp[4] * w; h1.y += bp[5] * w; h1.z += bp[6] * w; h1.w += bp[7] * w;
;         h2.x += bp[8] * w; h2.y += bp[9] * w; h2.z += bp[10] * w; h2.w += bp[11] * w; h3.x += bp[12] * w; h3.y += bp[13] * w; h3.z += bp[14] * w; h3.w += bp[15] * w;
;     }
	v_pk_mul_f32 v[52:53], v[16:17], v[108:109] op_sel_hi:[0,1]
	v_fmac_f32_e32 v211, v55, v83
	v_fmac_f32_e32 v153, v54, v90
	v_fmac_f32_e32 v157, v54, v94
	v_fmac_f32_e32 v165, v54, v102
	v_pk_fma_f32 v[38:39], v[38:39], v[0:1], v[40:41] op_sel_hi:[1,0,1]
	v_mul_f32_e32 v40, v191, v1
	v_pk_fma_f32 v[48:49], v[54:55], v[0:1], v[48:49] op_sel_hi:[1,0,1]
	v_pk_fma_f32 v[52:53], v[4:5], v[0:1], v[52:53] op_sel_hi:[1,0,1]
	v_sub_f32_e32 v1, v35, v50
	v_fmac_f32_e32 v153, v55, v91
	v_fmac_f32_e32 v157, v55, v95
	v_fmac_f32_e32 v165, v55, v103
	v_fmac_f32_e32 v211, v4, v56
	v_mul_f32_e32 v1, 0x3fb8aa3b, v1
	ds_read_b128 v[76:79], v207 offset:528
	ds_read_b128 v[80:83], v207 offset:544
	v_fmac_f32_e32 v211, v5, v57
	v_fmac_f32_e32 v153, v4, v12
	v_fmac_f32_e32 v157, v4, v20
	v_fmac_f32_e32 v165, v4, v8
	v_exp_f32_e32 v4, v1
	v_pk_mul_f32 v[54:55], v[16:17], v[110:111] op_sel_hi:[0,1]
	v_sub_f32_e32 v16, v35, v51
	v_fmac_f32_e32 v211, v6, v58
	v_mul_f32_e32 v16, 0x3fb8aa3b, v16
	v_fmac_f32_e32 v153, v5, v13
	v_fmac_f32_e32 v157, v5, v21
	v_fmac_f32_e32 v165, v5, v9
	v_fmac_f32_e32 v211, v7, v59
	ds_read_b128 v[56:59], v207 offset:560
	ds_read_b128 v[60:63], v207 offset:1024
	ds_read_b128 v[84:87], v207 offset:1040
	ds_read_b128 v[88:91], v207 offset:1056
	ds_read_b128 v[92:95], v207 offset:1072
	ds_read_b128 v[96:99], v207 offset:1536
	ds_read_b128 v[100:103], v207 offset:1552
	ds_read_b128 v[104:107], v207 offset:1568
	ds_read_b128 v[116:119], v207 offset:1584
	ds_read_b128 v[120:123], v207 offset:2048
	ds_read_b128 v[124:127], v207 offset:2064
	ds_read_b128 v[128:131], v207 offset:2080
	ds_read_b128 v[132:135], v207 offset:2096
	ds_read_b128 v[136:139], v207 offset:2560
	ds_read_b128 v[140:143], v207 offset:2576
	ds_read_b128 v[144:147], v207 offset:2592
	ds_read_b128 v[148:151], v207 offset:2608
	ds_read2st64_b32 v[8:9], v201 offset0:34 offset1:35
	ds_read2st64_b32 v[12:13], v201 offset0:36 offset1:37
	ds_read2st64_b32 v[20:21], v201 offset0:38 offset1:39
	v_exp_f32_e32 v16, v16
	v_pk_fma_f32 v[0:1], v[6:7], v[0:1], v[54:55] op_sel_hi:[1,0,1]
	v_mul_f32_e32 v4, v42, v4
	s_waitcnt lgkmcnt(14)
	v_pk_fma_f32 v[24:25], v[112:113], v[40:41], v[24:25] op_sel_hi:[1,0,1]
	v_pk_fma_f32 v[44:45], v[114:115], v[40:41], v[44:45] op_sel_hi:[1,0,1]
	v_pk_fma_f32 v[36:37], v[40:41], v[76:77], v[36:37] op_sel_hi:[0,1,1]
	v_pk_fma_f32 v[38:39], v[40:41], v[78:79], v[38:39] op_sel_hi:[0,1,1]
	v_pk_fma_f32 v[46:47], v[40:41], v[80:81], v[46:47] op_sel_hi:[0,1,1]
	v_pk_fma_f32 v[48:49], v[40:41], v[82:83], v[48:49] op_sel_hi:[0,1,1]
	v_pk_fma_f32 v[52:53], v[40:41], v[56:57], v[52:53] op_sel_hi:[0,1,1]
	v_pk_fma_f32 v[0:1], v[40:41], v[58:59], v[0:1] op_sel_hi:[0,1,1]
	s_waitcnt lgkmcnt(2)
	v_mul_f32_e32 v4, v8, v4
	v_pk_fma_f32 v[24:25], v[60:61], v[4:5], v[24:25] op_sel_hi:[1,0,1]
	v_pk_fma_f32 v[40:41], v[62:63], v[4:5], v[44:45] op_sel_hi:[1,0,1]
	v_pk_fma_f32 v[36:37], v[4:5], v[84:85], v[36:37] op_sel_hi:[0,1,1]
	v_pk_fma_f32 v[38:39], v[4:5], v[86:87], v[38:39] op_sel_hi:[0,1,1]
	v_pk_fma_f32 v[44:45], v[4:5], v[88:89], v[46:47] op_sel_hi:[0,1,1]
	v_pk_fma_f32 v[46:47], v[4:5], v[90:91], v[48:49] op_sel_hi:[0,1,1]
	v_pk_fma_f32 v[48:49], v[4:5], v[92:93], v[52:53] op_sel_hi:[0,1,1]
	v_pk_fma_f32 v[0:1], v[4:5], v[94:95], v[0:1] op_sel_hi:[0,1,1]
	v_mul_f32_e32 v4, v43, v16
	v_sub_f32_e32 v16, v35, v32
	v_mul_f32_e32 v16, 0x3fb8aa3b, v16
	v_exp_f32_e32 v16, v16
	v_mul_f32_e32 v4, v9, v4
	v_pk_fma_f32 v[24:25], v[96:97], v[4:5], v[24:25] op_sel_hi:[1,0,1]
	v_pk_fma_f32 v[40:41], v[98:99], v[4:5], v[40:41] op_sel_hi:[1,0,1]
	v_pk_fma_f32 v[36:37], v[4:5], v[100:101], v[36:37] op_sel_hi:[0,1,1]
	v_pk_fma_f32 v[38:39], v[4:5], v[102:103], v[38:39] op_sel_hi:[0,1,1]
	v_pk_fma_f32 v[42:43], v[4:5], v[104:105], v[44:45] op_sel_hi:[0,1,1]
	v_pk_fma_f32 v[44:45], v[4:5], v[106:107], v[46:47] op_sel_hi:[0,1,1]
	v_pk_fma_f32 v[46:47], v[4:5], v[116:117], v[48:49] op_sel_hi:[0,1,1]
	v_pk_fma_f32 v[0:1], v[4:5], v[118:119], v[0:1] op_sel_hi:[0,1,1]
	v_mul_f32_e32 v4, v28, v16
	v_sub_f32_e32 v16, v35, v33
	v_mul_f32_e32 v16, 0x3fb8aa3b, v16
	v_exp_f32_e32 v16, v16
	s_waitcnt lgkmcnt(1)
	v_mul_f32_e32 v4, v12, v4
	v_pk_fma_f32 v[24:25], v[120:121], v[4:5], v[24:25] op_sel_hi:[1,0,1]
	v_pk_fma_f32 v[40:41], v[122:123], v[4:5], v[40:41] op_sel_hi:[1,0,1]
	v_pk_fma_f32 v[36:37], v[4:5], v[124:125], v[36:37] op_sel_hi:[0,1,1]
	v_pk_fma_f32 v[38:39], v[4:5], v[126:127], v[38:39] op_sel_hi:[0,1,1]
	v_pk_fma_f32 v[42:43], v[4:5], v[128:129], v[42:43] op_sel_hi:[0,1,1]
	v_pk_fma_f32 v[32:33], v[4:5], v[130:131], v[44:45] op_sel_hi:[0,1,1]
	v_pk_fma_f32 v[44:45], v[4:5], v[132:133], v[46:47] op_sel_hi:[0,1,1]
	v_pk_fma_f32 v[0:1], v[4:5], v[134:135], v[0:1] op_sel_hi:[0,1,1]
	v_mul_f32_e32 v4, v29, v16
	v_sub_f32_e32 v16, v35, v34
	v_mul_f32_e32 v16, 0x3fb8aa3b, v16
	v_mul_f32_e32 v4, v13, v4
	v_exp_f32_e32 v16, v16
	v_pk_fma_f32 v[52:53], v[4:5], v[146:147], v[32:33] op_sel_hi:[0,1,1]
	ds_read_b128 v[32:35], v207 offset:3072
	v_pk_fma_f32 v[46:47], v[4:5], v[140:141], v[36:37] op_sel_hi:[0,1,1]
	v_pk_fma_f32 v[48:49], v[4:5], v[142:143], v[38:39] op_sel_hi:[0,1,1]
	ds_read_b128 v[36:39], v207 offset:3088
	v_pk_fma_f32 v[24:25], v[136:137], v[4:5], v[24:25] op_sel_hi:[1,0,1]
	v_pk_fma_f32 v[28:29], v[138:139], v[4:5], v[40:41] op_sel_hi:[1,0,1]
	v_pk_fma_f32 v[50:51], v[4:5], v[144:145], v[42:43] op_sel_hi:[0,1,1]
	v_pk_fma_f32 v[44:45], v[4:5], v[148:149], v[44:45] op_sel_hi:[0,1,1]
	v_pk_fma_f32 v[0:1], v[4:5], v[150:151], v[0:1] op_sel_hi:[0,1,1]
	v_mul_f32_e32 v4, v30, v16
	s_waitcnt lgkmcnt(2)
	v_mul_f32_e32 v4, v20, v4
	s_waitcnt lgkmcnt(1)
; __device__ __forceinline__ unsigned f2bf(float f) { return pk2(f, 0.f) & 0xffffu; }
; __device__ __forceinline__ float bf2f(bfu h) { return __uint_as_float((unsigned)h << 16); }
; __device__ __forceinline__ float silu_f(float x) { return x * __builtin_amdgcn_rcpf(1.f + __builtin_amdgcn_exp2f(x * -1.4426950408889634f)); }
; __device__ __forceinline__ void ssd_sample_unit(const Params& p, int unit, float* lds) {
;     ...
;     for (int l = 0; l < 8; ++l) {
;         const float* cp = Cf + l * 128 + nn * 16;
;         float part = cp[0] * h0.x + cp[1] * h0.y + cp[2] * h0.z + cp[3] * h0.w + cp[4] * h1.x + cp[5] * h1.y + cp[6] * h1.z + cp[7] * h1.w
;                    + cp[8] * h2.x + cp[9] * h2.y + cp[10] * h2.z + cp[11] * h2.w + cp[12] * h3.x + cp[13] * h3.y + cp[14] * h3.z + cp[15] * h3.w;
;         part += __shfl_xor(part, 1); part += __shfl_xor(part, 2); part += __shfl_xor(part, 4);
;         if (nn == l) myoff = part;
;     }
;     const float cs7 = csb[7], e7 = __expf(cs7);
;     h0.x *= e7; h0.y *= e7; h0.z *= e7; h0.w *= e7; h1.x *= e7; h1.y *= e7; h1.z *= e7; h1.w *= e7;
;     h2.x *= e7; h2.y *= e7; h2.z *= e7; h2.w *= e7; h3.x *= e7; h3.y *= e7; h3.z *= e7; h3.w *= e7;
; #pragma unroll
;     for (int l = 0; l < 8; ++l) {
;         const float w = __expf(cs7 - csb[l]) * dtb[l] * xsf[l * 64 + pp];
;         const float* bp = Bf + l * 128 + nn * 16;
;         h0.x += bp[0] * w; h0.y += bp[1] * w; h0.z += bp[2] * w; h0.w += bp[3] * w; h1.x += bp[4] * w; h1.y += bp[5] * w; h1.z += bp[6] * w; h1.w += bp[7] * w;
;         h2.x += bp[8] * w; h2.y += bp[9] * w; h2.z += bp[10] * w; h2.w += bp[11] * w; h3.x += bp[12] * w; h3.y += bp[13] * w; h3.z += bp[14] * w; h3.w += bp[15] * w;
;     }
;     float* so = p.out + O_SS + soff;
;     *(float4*)so = h0; *(float4*)(so + 4) = h1; *(float4*)(so + 8) = h2; *(float4*)(so + 12) = h3;
;     {
;         const int l = nn;
;         float y = myoff * __expf(csb[l]);
; #pragma unroll
;         for (int s = 0; s < 8; ++s) y += cbm[l * 8 + s] * xsf[s * 64 + pp];
;         y += p.d_skip[h] * xsf[l * 64 + pp];
;         const float z = bf2f(proj[(size_t)(row0 + l) * NPROJ + 3072 + h * 64 + pp]);
;         ((bfu*)(p.ws + WS_YG))[(size_t)(row0 + l) * 1024 + h * 64 + pp] = (bfu)f2bf(y * silu_f(z));
;     }
;     __syncthreads();
	v_pk_fma_f32 v[24:25], v[32:33], v[4:5], v[24:25] op_sel_hi:[1,0,1]
	ds_read_b128 v[40:43], v207 offset:3104
	v_pk_fma_f32 v[54:55], v[34:35], v[4:5], v[28:29] op_sel_hi:[1,0,1]
	ds_read_b128 v[32:35], v207 offset:3120
	s_waitcnt lgkmcnt(2)
	v_pk_fma_f32 v[46:47], v[4:5], v[36:37], v[46:47] op_sel_hi:[0,1,1]
	v_pk_fma_f32 v[48:49], v[4:5], v[38:39], v[48:49] op_sel_hi:[0,1,1]
	ds_read_b128 v[36:39], v207 offset:3584
	s_waitcnt lgkmcnt(2)
	v_pk_fma_f32 v[50:51], v[4:5], v[40:41], v[50:51] op_sel_hi:[0,1,1]
	v_pk_fma_f32 v[52:53], v[4:5], v[42:43], v[52:53] op_sel_hi:[0,1,1]
	s_waitcnt lgkmcnt(1)
	v_pk_fma_f32 v[56:57], v[4:5], v[32:33], v[44:45] op_sel_hi:[0,1,1]
	v_pk_fma_f32 v[0:1], v[4:5], v[34:35], v[0:1] op_sel_hi:[0,1,1]
	v_mul_f32_e32 v4, v156, v31
	v_mul_f32_e32 v4, v21, v4
	ds_read_b128 v[28:31], v207 offset:3600
	s_waitcnt lgkmcnt(1)
	v_pk_fma_f32 v[32:33], v[36:37], v[4:5], v[24:25] op_sel_hi:[1,0,1]
	ds_read_b128 v[40:43], v207 offset:3616
	v_pk_fma_f32 v[34:35], v[4:5], v[38:39], v[54:55] op_sel_hi:[0,1,1]
	ds_read_b128 v[36:39], v207 offset:3632
	s_waitcnt lgkmcnt(2)
	v_pk_fma_f32 v[28:29], v[4:5], v[28:29], v[46:47] op_sel_hi:[0,1,1]
	v_pk_fma_f32 v[30:31], v[4:5], v[30:31], v[48:49] op_sel_hi:[0,1,1]
	s_waitcnt lgkmcnt(1)
	v_pk_fma_f32 v[40:41], v[4:5], v[40:41], v[50:51] op_sel_hi:[0,1,1]
	v_pk_fma_f32 v[42:43], v[4:5], v[42:43], v[52:53] op_sel_hi:[0,1,1]
	s_waitcnt lgkmcnt(0)
	v_pk_fma_f32 v[38:39], v[4:5], v[38:39], v[0:1] op_sel_hi:[0,1,1]
	v_add_co_u32_e64 v0, s[28:29], s3, v192
	ds_read_b128 v[44:47], v208 offset:10240
	s_nop 0
	v_addc_co_u32_e64 v1, s[28:29], 0, v193, s[28:29]
	v_pk_fma_f32 v[36:37], v[4:5], v[36:37], v[56:57] op_sel_hi:[0,1,1]
	global_store_dwordx4 v[0:1], v[32:35], off
	global_store_dwordx4 v[0:1], v[28:31], off offset:16
	global_store_dwordx4 v[0:1], v[40:43], off offset:32
	global_store_dwordx4 v[0:1], v[36:39], off offset:48
	v_or_b32_e32 v4, s51, v198
	v_mov_b64_e32 v[0:1], s[34:35]
	v_mad_i64_i32 v[0:1], s[28:29], v4, s33, v[0:1]
	v_lshl_add_u64 v[0:1], v[0:1], 0, s[4:5]
	v_lshl_add_u64 v[0:1], v[0:1], 0, v[188:189]
	global_load_ushort v24, v[0:1], off
	s_lshl_b32 s28, s50, 2
	v_mov_b32_e32 v16, s28
	global_load_dword v16, v16, s[30:31]
	ds_bpermute_b32 v154, v205, v152
	ds_bpermute_b32 v155, v204, v211
	v_fmac_f32_e32 v212, v6, v26
	v_fmac_f32_e32 v169, v5, v17
	v_fmac_f32_e32 v212, v7, v27
	s_waitcnt lgkmcnt(1)
	v_add_f32_e32 v0, v152, v154
	s_waitcnt lgkmcnt(0)
	v_add_f32_e32 v5, v211, v155
	ds_bpermute_b32 v1, v206, v0
	ds_bpermute_b32 v17, v205, v5
	ds_bpermute_b32 v25, v204, v212
	v_fmac_f32_e32 v153, v6, v14
	v_fmac_f32_e32 v153, v7, v15
	v_fmac_f32_e32 v157, v6, v22
	s_waitcnt lgkmcnt(2)
	v_add_f32_e32 v0, v0, v1
	s_waitcnt lgkmcnt(1)
	v_add_f32_e32 v1, v5, v17
	s_waitcnt lgkmcnt(0)
	v_add_f32_e32 v17, v212, v25
	ds_bpermute_b32 v14, v204, v153
	v_fmac_f32_e32 v157, v7, v23
	v_fmac_f32_e32 v161, v6, v2
	ds_bpermute_b32 v25, v205, v17
	ds_bpermute_b32 v15, v204, v157
	v_fmac_f32_e32 v161, v7, v3
	v_fmac_f32_e32 v165, v6, v10
	ds_bpermute_b32 v2, v204, v161
	v_fmac_f32_e32 v165, v7, v11
	v_fmac_f32_e32 v169, v6, v18
	ds_bpermute_b32 v3, v204, v165
	v_fmac_f32_e32 v169, v7, v19
	ds_bpermute_b32 v6, v204, v169
	s_waitcnt lgkmcnt(5)
	v_add_f32_e32 v14, v153, v14
	s_waitcnt lgkmcnt(4)
	v_add_f32_e32 v17, v17, v25
	ds_bpermute_b32 v23, v205, v14
	s_waitcnt lgkmcnt(4)
	v_add_f32_e32 v15, v157, v15
	ds_bpermute_b32 v5, v206, v1
	ds_bpermute_b32 v22, v206, v17
	ds_bpermute_b32 v25, v205, v15
	s_waitcnt lgkmcnt(6)
	v_add_f32_e32 v2, v161, v2
	ds_bpermute_b32 v7, v205, v2
	s_waitcnt lgkmcnt(6)
	v_add_f32_e32 v3, v165, v3
	ds_bpermute_b32 v10, v205, v3
	s_waitcnt lgkmcnt(6)
	v_add_f32_e32 v6, v169, v6
	ds_bpermute_b32 v11, v205, v6
	s_waitcnt lgkmcnt(6)
	v_add_f32_e32 v14, v14, v23
	s_waitcnt lgkmcnt(5)
	v_add_f32_e32 v1, v1, v5
	s_waitcnt lgkmcnt(4)
	v_add_f32_e32 v5, v17, v22
	ds_bpermute_b32 v17, v206, v14
	s_waitcnt lgkmcnt(4)
	v_add_f32_e32 v15, v15, v25
	ds_bpermute_b32 v22, v206, v15
	s_waitcnt lgkmcnt(4)
	v_add_f32_e32 v2, v2, v7
	ds_bpermute_b32 v7, v206, v2
	s_waitcnt lgkmcnt(4)
	v_add_f32_e32 v3, v3, v10
	ds_bpermute_b32 v10, v206, v3
	s_waitcnt lgkmcnt(4)
	v_add_f32_e32 v6, v6, v11
	v_cndmask_b32_e64 v0, 0, v0, s[12:13]
	ds_bpermute_b32 v11, v206, v6
	v_cndmask_b32_e64 v0, v0, v1, s[14:15]
	s_waitcnt lgkmcnt(4)
	v_add_f32_e32 v14, v14, v17
	v_cndmask_b32_e64 v0, v0, v5, s[16:17]
	s_waitcnt lgkmcnt(3)
	v_add_f32_e32 v15, v15, v22
	v_cndmask_b32_e64 v0, v0, v14, s[18:19]
	v_mul_f32_e32 v1, 0x3fb8aa3b, v210
	s_waitcnt lgkmcnt(2)
	v_add_f32_e32 v2, v2, v7
	v_cndmask_b32_e64 v0, v0, v15, s[20:21]
	v_exp_f32_e32 v5, v1
	s_waitcnt lgkmcnt(1)
	v_add_f32_e32 v3, v3, v10
	v_cndmask_b32_e64 v0, v0, v2, s[22:23]
	s_waitcnt lgkmcnt(0)
	v_add_f32_e32 v6, v6, v11
	v_cndmask_b32_e64 v0, v0, v3, s[24:25]
	v_cndmask_b32_e64 v10, v0, v6, s[26:27]
	v_pk_mul_f32 v[6:7], v[190:191], v[44:45]
	ds_read_b128 v[0:3], v208 offset:10256
	v_fma_f32 v5, v10, v5, v6
	v_add_f32_e32 v5, v7, v5
	v_pk_mul_f32 v[6:7], v[8:9], v[46:47]
	s_add_u32 s38, s38, s36
	v_add_f32_e32 v5, v6, v5
	v_add_f32_e32 v5, v7, v5
	s_waitcnt vmcnt(1)
	v_lshlrev_b32_e32 v7, 16, v24
	v_mul_f32_e32 v8, 0xbfb8aa3b, v7
	v_exp_f32_e32 v8, v8
	ds_read_b32 v6, v209 offset:8192
	s_waitcnt lgkmcnt(1)
	v_pk_mul_f32 v[0:1], v[12:13], v[0:1]
	s_addc_u32 s39, s39, s37
	v_add_f32_e32 v0, v0, v5
	v_add_f32_e32 v5, v1, v0
	v_pk_mul_f32 v[0:1], v[20:21], v[2:3]
	v_add_f32_e32 v2, 1.0, v8
	v_rcp_f32_e32 v17, v2
	v_add_f32_e32 v0, v0, v5
	v_add_f32_e32 v2, v1, v0
	v_ashrrev_i32_e32 v5, 31, v4
	s_waitcnt vmcnt(0) lgkmcnt(0)
	v_pk_mul_f32 v[0:1], v[16:17], v[6:7]
	s_cmpk_lt_i32 s41, 0x200
	v_add_f32_e32 v0, v2, v0
	v_mul_f32_e32 v0, v0, v1
	v_cvt_pk_bf16_f32 v2, v0, s0
	v_lshlrev_b64 v[0:1], 11, v[4:5]
	v_lshl_add_u64 v[0:1], s[0:1], 0, v[0:1]
	v_lshl_add_u64 v[0:1], v[0:1], 0, s[4:5]
	v_lshl_add_u64 v[0:1], v[0:1], 0, v[188:189]
	global_store_short v[0:1], v2, off
	s_barrier
	s_cbranch_scc0 .LBB0_413
; __device__ __forceinline__ float bflo(unsigned u) { return __uint_as_float(u << 16); }
; __device__ __forceinline__ float bfhi(unsigned u) { return __uint_as_float(u & 0xffff0000u); }
; __device__ __forceinline__ float bf2f(bfu h) { return __uint_as_float((unsigned)h << 16); }
; __device__ __forceinline__ void ssd_sample_unit(const Params& p, int unit, float* lds) {
;     const int h = unit & 15, b = unit >> 4, g = h >> 2, tid = threadIdx.x;
;     float* Bf = lds; float* Cf = Bf + 1024; float* xsf = Cf + 1024; float* cbm = xsf + 512; float* csb = cbm + 64; float* dtb = csb + 8;
;     const int row0 = MP + b * 8;
;     const bfu* xbc = (const bfu*)(p.ws + WS_XBC);
;     const bfu* proj = (const bfu*)(p.ws + WS_PROJ);
;     {
;         const int l = tid >> 6, n2 = (tid & 63) * 2;
;         const unsigned ub = *(const unsigned*)(xbc + (size_t)(row0 + l) * 2048 + 1024 + g * 128 + n2);
;         const unsigned uc = *(const unsigned*)(xbc + (size_t)(row0 + l) * 2048 + 1536 + g * 128 + n2);
;         Bf[l * 128 + n2] = bflo(ub); Bf[l * 128 + n2 + 1] = bfhi(ub); Cf[l * 128 + n2] = bflo(uc); Cf[l * 128 + n2 + 1] = bfhi(uc);
;         xsf[tid] = bf2f(xbc[(size_t)(row0 + l) * 2048 + h * 64 + (tid & 63)]);
;         if (tid < 8) dtb[tid] = ((const float*)(p.ws + WS_DT))[(size_t)(row0 + tid) * 16 + h];
;     }
;     __syncthreads();
;     if (tid == 0) { const float a = -__expf(p.a_log[h]); float run = 0.f; for (int l = 0; l < 8; ++l) { run += dtb[l] * a; csb[l] = run; } }
;     __syncthreads();
;     if (tid < 64) {
;         const int l = tid >> 3, s = tid & 7;
;         float d = 0.f;
;         if (s <= l) { for (int n = 0; n < 128; ++n) d += Cf[l * 128 + n] * Bf[s * 128 + n]; d *= __expf(csb[l] - csb[s]) * dtb[s]; }
;         cbm[tid] = d;
;     }
;     __syncthreads();
;     const int pp = tid >> 3, nn = tid & 7;
;     const size_t soff = ((size_t)(b * 16 + h) * 64 + pp) * 128 + nn * 16;
;     const float* hp = p.state_ssm + soff;
;     float4 h0 = *(const float4*)hp, h1 = *(const float4*)(hp + 4), h2 = *(const float4*)(hp + 8), h3 = *(const float4*)(hp + 12);
.LBB0_406:
	s_ashr_i32 s4, s41, 1
	s_and_b32 s51, s4, -8
	s_addk_i32 s51, 0x4000
	v_add_u32_e32 v0, s51, v194
	v_ashrrev_i32_e32 v1, 31, v0
	v_lshlrev_b64 v[0:1], 12, v[0:1]
	s_lshl_b32 s4, s41, 6
	v_lshl_add_u64 v[0:1], s[48:49], 0, v[0:1]
	s_and_b32 s4, s4, 0x300
	s_and_b32 s50, s41, 15
	v_lshl_add_u64 v[2:3], v[0:1], 0, s[4:5]
	v_lshl_add_u64 v[2:3], v[2:3], 0, v[182:183]
	s_lshl_b32 s52, s50, 6
	global_load_dword v4, v[2:3], off offset:2048
	global_load_dword v5, v[2:3], off offset:3072
	v_or_b32_e32 v2, s52, v179
	v_lshlrev_b32_e32 v2, 1, v2
	v_mov_b32_e32 v3, v183
	v_lshl_add_u64 v[0:1], v[0:1], 0, v[2:3]
	global_load_ushort v6, v[0:1], off
	s_lshl_b32 s98, s50, 2
	v_mov_b32_e32 v233, s98
	global_load_dword v232, v233, s[44:45]
	s_waitcnt vmcnt(3)
	v_lshlrev_b32_e32 v0, 16, v4
	v_and_b32_e32 v1, 0xffff0000, v4
	s_waitcnt vmcnt(2)
	v_lshlrev_b32_e32 v2, 16, v5
	v_and_b32_e32 v3, 0xffff0000, v5
	s_waitcnt vmcnt(1)
	v_lshlrev_b32_e32 v4, 16, v6
	ds_write2st64_b64 v197, v[0:1], v[2:3] offset1:8
	ds_write_b32 v173, v4 offset:8192
	s_and_saveexec_b64 s[28:29], vcc
	s_cbranch_execz .LBB0_408
	v_or_b32_e32 v0, s51, v172
	v_ashrrev_i32_e32 v1, 31, v0
	v_lshlrev_b64 v[0:1], 6, v[0:1]
	v_lshl_add_u64 v[0:1], s[46:47], 0, v[0:1]
	s_lshl_b32 s4, s50, 2
	v_lshl_add_u64 v[0:1], v[0:1], 0, s[4:5]
	global_load_dword v0, v[0:1], off
	s_waitcnt vmcnt(0)
	ds_write_b32 v173, v0 offset:10528
.LBB0_408:
	s_or_b64 exec, exec, s[28:29]
	s_waitcnt lgkmcnt(0)
	s_barrier
	s_mov_b64 s[28:29], exec
	v_readlane_b32 s42, v252, 6
	v_readlane_b32 s43, v252, 7
	s_and_b64 s[42:43], s[28:29], s[42:43]
	s_mov_b64 exec, s[42:43]
	s_cbranch_execz .LBB0_410
	s_lshl_b32 s4, s50, 2
	v_mov_b32_e32 v0, s4
	s_waitcnt vmcnt(0)
	v_mov_b32_e32 v4, v232
	ds_read_b128 v[0:3], v183 offset:10528
	s_waitcnt vmcnt(0)
	v_mul_f32_e32 v4, 0x3fb8aa3b, v4
	v_exp_f32_e32 v8, v4
	ds_read_b128 v[4:7], v183 offset:10544
	s_waitcnt lgkmcnt(1)
	v_fma_f32 v0, -v0, v8, 0
	v_fma_f32 v1, -v8, v1, v0
	v_fma_f32 v2, -v8, v2, v1
	v_fma_f32 v3, -v8, v3, v2
	ds_write_b128 v183, v[0:3] offset:10496
	s_waitcnt lgkmcnt(1)
	v_fma_f32 v0, -v8, v4, v3
	v_fma_f32 v1, -v8, v5, v0
	v_fma_f32 v2, -v8, v6, v1
	v_fma_f32 v3, -v8, v7, v2
	ds_write_b128 v183, v[0:3] offset:10512
.LBB0_410:
	s_or_b64 exec, exec, s[28:29]
	v_lshl_add_u64 v[214:215], v[186:187], 0, s[38:39]
	global_load_dwordx4 v[216:219], v[214:215], off
	global_load_dwordx4 v[220:223], v[214:215], off offset:16
	global_load_dwordx4 v[224:227], v[214:215], off offset:32
	global_load_dwordx4 v[228:231], v[214:215], off offset:48
	s_waitcnt lgkmcnt(0)
	s_barrier
	s_and_saveexec_b64 s[28:29], s[8:9]
	s_cbranch_execz .LBB0_405
	v_mov_b32_e32 v0, 0
	s_and_saveexec_b64 s[42:43], s[10:11]
	s_cbranch_execz .LBB0_404
	ds_read_b128 v[20:23], v199 offset:4096
	ds_read_b128 v[12:15], v199 offset:4112
	ds_read_b128 v[8:11], v199 offset:4128
	ds_read_b128 v[0:3], v199 offset:4144
	ds_read_b128 v[28:31], v200
	ds_read_b128 v[24:27], v200 offset:16
	ds_read_b128 v[16:19], v200 offset:32
	ds_read_b128 v[4:7], v200 offset:48
	ds_read_b32 v32, v199 offset:4604
	s_waitcnt lgkmcnt(4)
	v_fma_f32 v20, v20, v28, 0
	v_fmac_f32_e32 v20, v21, v29
	v_fmac_f32_e32 v20, v22, v30
	v_fmac_f32_e32 v20, v23, v31
	s_waitcnt lgkmcnt(3)
	v_fmac_f32_e32 v20, v12, v24
	v_fmac_f32_e32 v20, v13, v25
	v_fmac_f32_e32 v20, v14, v26
	v_fmac_f32_e32 v20, v15, v27
	s_waitcnt lgkmcnt(2)
	v_fmac_f32_e32 v20, v8, v16
	v_fmac_f32_e32 v20, v9, v17
	v_fmac_f32_e32 v20, v10, v18
	v_fmac_f32_e32 v20, v11, v19
	ds_read_b128 v[8:11], v200 offset:64
	ds_read_b128 v[12:15], v199 offset:4160
	s_waitcnt lgkmcnt(3)
	v_fmac_f32_e32 v20, v0, v4
	v_fmac_f32_e32 v20, v1, v5
	v_fmac_f32_e32 v20, v2, v6
	v_fmac_f32_e32 v20, v3, v7
	ds_read_b128 v[0:3], v199 offset:4176
	ds_read_b128 v[4:7], v200 offset:80
	s_waitcnt lgkmcnt(2)
	v_fmac_f32_e32 v20, v12, v8
	v_fmac_f32_e32 v20, v13, v9
	v_fmac_f32_e32 v20, v14, v10
	v_fmac_f32_e32 v20, v15, v11
	ds_read_b128 v[8:11], v200 offset:96
	ds_read_b128 v[12:15], v199 offset:4192
	s_waitcnt lgkmcnt(2)
	v_fmac_f32_e32 v20, v0, v4
	v_fmac_f32_e32 v20, v1, v5
	v_fmac_f32_e32 v20, v2, v6
	v_fmac_f32_e32 v20, v3, v7
	ds_read_b128 v[0:3], v199 offset:4208
	ds_read_b128 v[4:7], v200 offset:112
	s_waitcnt lgkmcnt(2)
	v_fmac_f32_e32 v20, v12, v8
	v_fmac_f32_e32 v20, v13, v9
	v_fmac_f32_e32 v20, v14, v10
	v_fmac_f32_e32 v20, v15, v11
	ds_read_b128 v[8:11], v200 offset:128
	ds_read_b128 v[12:15], v199 offset:4224
	s_waitcnt lgkmcnt(2)
	v_fmac_f32_e32 v20, v0, v4
	v_fmac_f32_e32 v20, v1, v5
	v_fmac_f32_e32 v20, v2, v6
	v_fmac_f32_e32 v20, v3, v7
	ds_read_b128 v[0:3], v199 offset:4240
	ds_read_b128 v[4:7], v200 offset:144
	s_waitcnt lgkmcnt(2)
	v_fmac_f32_e32 v20, v12, v8
	v_fmac_f32_e32 v20, v13, v9
	v_fmac_f32_e32 v20, v14, v10
	v_fmac_f32_e32 v20, v15, v11
	ds_read_b128 v[8:11], v200 offset:160
	ds_read_b128 v[12:15], v199 offset:4256
	s_waitcnt lgkmcnt(2)
	v_fmac_f32_e32 v20, v0, v4
	v_fmac_f32_e32 v20, v1, v5
	v_fmac_f32_e32 v20, v2, v6
	v_fmac_f32_e32 v20, v3, v7
	ds_read_b128 v[0:3], v199 offset:4272
	ds_read_b128 v[4:7], v200 offset:176
	s_waitcnt lgkmcnt(2)
	v_fmac_f32_e32 v20, v12, v8
	v_fmac_f32_e32 v20, v13, v9
	v_fmac_f32_e32 v20, v14, v10
	v_fmac_f32_e32 v20, v15, v11
	ds_read_b128 v[8:11], v200 offset:192
	ds_read_b128 v[12:15], v199 offset:4288
	s_waitcnt lgkmcnt(2)
; __device__ __forceinline__ void ssd_sample_unit(const Params& p, int unit, float* lds) {
;     ...
;     if (tid < 64) {
;         const int l = tid >> 3, s = tid & 7;
;         float d = 0.f;
;         if (s <= l) { for (int n = 0; n < 128; ++n) d += Cf[l * 128 + n] * Bf[s * 128 + n]; d *= __expf(csb[l] - csb[s]) * dtb[s]; }
;         cbm[tid] = d;
;     }
	v_fmac_f32_e32 v20, v0, v4
	v_fmac_f32_e32 v20, v1, v5
	v_fmac_f32_e32 v20, v2, v6
	v_fmac_f32_e32 v20, v3, v7
	ds_read_b128 v[0:3], v199 offset:4304
	ds_read_b128 v[4:7], v200 offset:208
	s_waitcnt lgkmcnt(2)
	v_fmac_f32_e32 v20, v12, v8
	v_fmac_f32_e32 v20, v13, v9
	v_fmac_f32_e32 v20, v14, v10
	v_fmac_f32_e32 v20, v15, v11
	ds_read_b128 v[8:11], v200 offset:224
	ds_read_b128 v[12:15], v199 offset:4320
	s_waitcnt lgkmcnt(2)
	v_fmac_f32_e32 v20, v0, v4
	v_fmac_f32_e32 v20, v1, v5
	v_fmac_f32_e32 v20, v2, v6
	v_fmac_f32_e32 v20, v3, v7
	ds_read_b128 v[0:3], v199 offset:4336
	ds_read_b128 v[4:7], v200 offset:240
	s_waitcnt lgkmcnt(2)
	v_fmac_f32_e32 v20, v12, v8
	v_fmac_f32_e32 v20, v13, v9
	v_fmac_f32_e32 v20, v14, v10
	v_fmac_f32_e32 v20, v15, v11
	ds_read_b128 v[8:11], v200 offset:256
	ds_read_b128 v[12:15], v199 offset:4352
	s_waitcnt lgkmcnt(2)
	v_fmac_f32_e32 v20, v0, v4
	v_fmac_f32_e32 v20, v1, v5
	v_fmac_f32_e32 v20, v2, v6
	v_fmac_f32_e32 v20, v3, v7
	ds_read_b128 v[0:3], v199 offset:4368
	ds_read_b128 v[4:7], v200 offset:272
	s_waitcnt lgkmcnt(2)
	v_fmac_f32_e32 v20, v12, v8
	v_fmac_f32_e32 v20, v13, v9
	v_fmac_f32_e32 v20, v14, v10
	v_fmac_f32_e32 v20, v15, v11
	ds_read_b128 v[8:11], v200 offset:288
	ds_read_b128 v[12:15], v199 offset:4384
	s_waitcnt lgkmcnt(2)
	v_fmac_f32_e32 v20, v0, v4
	v_fmac_f32_e32 v20, v1, v5
	v_fmac_f32_e32 v20, v2, v6
	v_fmac_f32_e32 v20, v3, v7
	ds_read_b128 v[0:3], v199 offset:4400
	ds_read_b128 v[4:7], v200 offset:304
	s_waitcnt lgkmcnt(2)
	v_fmac_f32_e32 v20, v12, v8
	v_fmac_f32_e32 v20, v13, v9
	v_fmac_f32_e32 v20, v14, v10
	v_fmac_f32_e32 v20, v15, v11
	ds_read_b128 v[8:11], v200 offset:320
	ds_read_b128 v[12:15], v199 offset:4416
	s_waitcnt lgkmcnt(2)
	v_fmac_f32_e32 v20, v0, v4
	v_fmac_f32_e32 v20, v1, v5
	v_fmac_f32_e32 v20, v2, v6
	v_fmac_f32_e32 v20, v3, v7
	ds_read_b128 v[0:3], v199 offset:4432
	ds_read_b128 v[4:7], v200 offset:336
	s_waitcnt lgkmcnt(2)
	v_fmac_f32_e32 v20, v12, v8
	v_fmac_f32_e32 v20, v13, v9
	v_fmac_f32_e32 v20, v14, v10
	v_fmac_f32_e32 v20, v15, v11
	ds_read_b128 v[8:11], v200 offset:352
	ds_read_b128 v[12:15], v199 offset:4448
	s_waitcnt lgkmcnt(2)
	v_fmac_f32_e32 v20, v0, v4
	v_fmac_f32_e32 v20, v1, v5
	v_fmac_f32_e32 v20, v2, v6
	v_fmac_f32_e32 v20, v3, v7
	ds_read_b128 v[0:3], v199 offset:4464
	ds_read_b128 v[4:7], v200 offset:368
	s_waitcnt lgkmcnt(2)
	v_fmac_f32_e32 v20, v12, v8
	v_fmac_f32_e32 v20, v13, v9
	v_fmac_f32_e32 v20, v14, v10
	v_fmac_f32_e32 v20, v15, v11
	ds_read_b128 v[8:11], v200 offset:384
	ds_read_b128 v[12:15], v199 offset:4480
	s_waitcnt lgkmcnt(2)
	v_fmac_f32_e32 v20, v0, v4
	v_fmac_f32_e32 v20, v1, v5
	v_fmac_f32_e32 v20, v2, v6
	v_fmac_f32_e32 v20, v3, v7
	ds_read_b128 v[0:3], v199 offset:4496
	ds_read_b128 v[4:7], v200 offset:400
	s_waitcnt lgkmcnt(2)
	v_fmac_f32_e32 v20, v12, v8
	v_fmac_f32_e32 v20, v13, v9
	v_fmac_f32_e32 v20, v14, v10
	v_fmac_f32_e32 v20, v15, v11
	ds_read_b128 v[8:11], v200 offset:416
	ds_read_b128 v[12:15], v199 offset:4512
	s_waitcnt lgkmcnt(2)
	v_fmac_f32_e32 v20, v0, v4
	v_fmac_f32_e32 v20, v1, v5
	v_fmac_f32_e32 v20, v2, v6
	v_fmac_f32_e32 v20, v3, v7
	ds_read_b128 v[0:3], v199 offset:4528
	ds_read_b128 v[4:7], v200 offset:432
	s_waitcnt lgkmcnt(2)
	v_fmac_f32_e32 v20, v12, v8
	v_fmac_f32_e32 v20, v13, v9
	v_fmac_f32_e32 v20, v14, v10
	v_fmac_f32_e32 v20, v15, v11
	ds_read_b128 v[8:11], v200 offset:448
	ds_read_b128 v[12:15], v199 offset:4544
	s_waitcnt lgkmcnt(2)
	v_fmac_f32_e32 v20, v0, v4
	v_fmac_f32_e32 v20, v1, v5
	v_fmac_f32_e32 v20, v2, v6
	ds_read_b96 v[0:2], v199 offset:4560
	ds_read_b96 v[4:6], v200 offset:464
	v_fmac_f32_e32 v20, v3, v7
	s_waitcnt lgkmcnt(2)
	v_fmac_f32_e32 v20, v12, v8
	v_fmac_f32_e32 v20, v13, v9
	v_fmac_f32_e32 v20, v14, v10
	v_fmac_f32_e32 v20, v15, v11
	s_waitcnt lgkmcnt(1)
	v_mov_b32_e32 v8, v1
	v_mov_b32_e32 v9, v2
	s_waitcnt lgkmcnt(0)
	v_mov_b32_e32 v10, v5
	v_mov_b32_e32 v11, v6
	v_fmac_f32_e32 v20, v0, v4
	v_pk_mul_f32 v[0:1], v[8:9], v[10:11]
	ds_read2_b32 v[2:3], v200 offset0:119 offset1:120
	v_add_f32_e32 v0, v20, v0
	v_add_f32_e32 v8, v0, v1
	v_add_u32_e32 v0, 0x11dc, v199
	ds_read2_b32 v[0:1], v0 offset1:1
	v_add_u32_e32 v4, 0x11e4, v199
	v_add_u32_e32 v6, 0x11ec, v199
	ds_read2_b32 v[4:5], v4 offset1:1
	ds_read2_b32 v[6:7], v6 offset1:1
	ds_read_b32 v11, v201 offset:10496
	s_waitcnt lgkmcnt(3)
	v_pk_mul_f32 v[0:1], v[0:1], v[2:3]
	ds_read2_b32 v[2:3], v200 offset0:121 offset1:122
	v_add_f32_e32 v0, v8, v0
	v_add_f32_e32 v12, v0, v1
	ds_read2_b32 v[0:1], v200 offset0:123 offset1:124
	ds_read2_b32 v[8:9], v200 offset0:125 offset1:126
	ds_read_b32 v10, v200 offset:508
	s_waitcnt lgkmcnt(3)
	v_pk_mul_f32 v[2:3], v[4:5], v[2:3]
	s_nop 0
	v_add_f32_e32 v2, v12, v2
	v_add_f32_e32 v12, v2, v3
	v_add_u32_e32 v2, 0x11f4, v199
	v_add_u32_e32 v4, 0x2800, v202
	ds_read2_b32 v[2:3], v2 offset1:1
	ds_read2_b32 v[4:5], v4 offset0:64 offset1:72
	s_waitcnt lgkmcnt(4)
	v_pk_mul_f32 v[0:1], v[6:7], v[0:1]
	s_waitcnt lgkmcnt(0)
	v_mov_b32_e32 v33, v5
	v_add_f32_e32 v0, v12, v0
	v_add_f32_e32 v6, v0, v1
	v_pk_mul_f32 v[0:1], v[2:3], v[8:9]
	v_sub_f32_e32 v2, v11, v4
	v_mul_f32_e32 v2, 0x3fb8aa3b, v2
	v_exp_f32_e32 v11, v2
	v_add_f32_e32 v0, v6, v0
	v_add_f32_e32 v2, v0, v1
	v_pk_mul_f32 v[0:1], v[32:33], v[10:11]
	s_nop 0
	v_add_f32_e32 v0, v2, v0
	v_mul_f32_e32 v0, v0, v1
	s_branch .LBB0_404
